# attention: static priority asymmetry (waves 0-3 raised) held for the whole attention phase instead of only the fast loops
# speedup vs baseline: 1.0002x; 1.0002x over previous
; #define LAS __attribute__((address_space(3)))
; __device__ __forceinline__ float ret_lg(int h) { const float x = __builtin_ldexpf(1.f, -5 - h); return -x * (1.f + x * (0.5f + x * (0.33333334f + x * (0.25f + x * 0.2f)))); }
; #define REP(j) for (int rep_ = 0; rep_ < (((DUP_MASK >> (j)) & 1) ? 2 : 1); ++rep_)
; __device__ __forceinline__ void ret_scan(const float* kv, bf16* rp, ldsp lds, int tid, int G) {
;     LAS float* carry = (LAS float*)lds;
;     const int e = tid & 255, half = tid >> 8;
;     for (int base = blockIdx.x * 256; base < 65536; base += G * 256) {
;         const int idx = base + e;
;         const float lg = ret_lg(idx >> 13), gam = expf(lg), cd = expf(128.f * lg);
;         float kvv[32];
; #pragma unroll
;         for (int i = 0; i < 32; ++i) kvv[i] = kv[(size_t)(32 * half + i) * 65536 + idx];
; __global__ void __launch_bounds__(512, 2) fwd_mega(Args a) {
;     ...
;         if (IN(pb + 3)) REP(3) { PHASE_BEGIN
;             const bf16* PROJ = (const bf16*)(ws + WS_PROJ);
;             ret_scan((const float*)(ws + WS_KV), (bf16*)(ws + WS_RP), lds, tid, G);
.LBB0_411:
	s_andn2_b64 vcc, exec, s[0:1]
	s_cbranch_vccnz .LBB0_537
	v_readfirstlane_b32 s100, v196
	s_lshr_b32 s100, s100, 8
	s_cmp_lg_u32 s100, 0
	s_cbranch_scc1 .Lap_skip
	s_setprio 1
.Lap_skip:
	v_readlane_b32 s16, v254, 0
	v_readlane_b32 s17, v254, 1
	v_mov_b32_e32 v0, v196
	s_load_dwordx2 s[12:13], s[16:17], 0x78
	v_readlane_b32 s0, v254, 20
	v_readlane_b32 s1, v254, 21
	s_andn2_b64 vcc, exec, s[0:1]
	v_readfirstlane_b32 s47, v0
	s_cbranch_vccnz .LBB0_419
	s_waitcnt lgkmcnt(0)
	s_add_u32 s14, s12, 0x35000000
	s_addc_u32 s15, s13, 0
	s_add_u32 s18, s12, 0x36000000
	s_addc_u32 s19, s13, 0
	s_add_u32 s20, s12, 0x36400000
	s_addc_u32 s21, s13, 0
	s_add_u32 s22, s12, 0x36420000
	s_addc_u32 s23, s13, 0
	s_add_u32 s24, s12, 0x36440000
	s_addc_u32 s25, s13, 0
	s_add_u32 s26, s12, 0x36460000
	s_addc_u32 s27, s13, 0
	s_add_u32 s28, s12, 0x36480000
	s_addc_u32 s29, s13, 0
	s_add_u32 s30, s12, 0x364a0000
	s_addc_u32 s31, s13, 0
	s_add_u32 s34, s12, 0x364c0000
	s_addc_u32 s35, s13, 0
	s_add_u32 s36, s12, 0x364e0000
	s_addc_u32 s37, s13, 0
	s_add_u32 s38, s12, 0x36500000
	s_addc_u32 s39, s13, 0
	s_add_u32 s40, s12, 0x36520000
	s_addc_u32 s41, s13, 0
	s_add_u32 s48, s12, 0x36540000
	s_addc_u32 s49, s13, 0
	s_add_u32 s56, s12, 0x36560000
	s_addc_u32 s57, s13, 0
	s_add_u32 s62, s12, 0x36580000
	s_addc_u32 s63, s13, 0
	s_add_u32 s64, s12, 0x365a0000
	s_addc_u32 s65, s13, 0
	s_add_u32 s66, s12, 0x365c0000
	s_addc_u32 s67, s13, 0
	s_add_u32 s74, s12, 0x365e0000
	s_addc_u32 s75, s13, 0
	s_add_u32 s76, s12, 0x36600000
	s_addc_u32 s77, s13, 0
	s_add_u32 s78, s12, 0x36620000
	s_addc_u32 s79, s13, 0
	s_add_u32 s82, s12, 0x36640000
	s_addc_u32 s83, s13, 0
	s_add_u32 s84, s12, 0x36660000
	s_addc_u32 s85, s13, 0
	s_add_u32 s88, s12, 0x36680000
	s_addc_u32 s89, s13, 0
	s_add_u32 s90, s12, 0x366a0000
	s_addc_u32 s91, s13, 0
	s_add_u32 s92, s12, 0x366c0000
	s_addc_u32 s93, s13, 0
	s_add_u32 s80, s12, 0x366e0000
	s_addc_u32 s81, s13, 0
	s_add_u32 s42, s12, 0x36700000
	s_addc_u32 s43, s13, 0
	s_add_u32 s4, s12, 0x36720000
	s_addc_u32 s5, s13, 0
	s_add_u32 s60, s12, 0x36740000
	s_addc_u32 s61, s13, 0
	s_add_u32 s58, s12, 0x36760000
	s_addc_u32 s59, s13, 0
	s_add_u32 s54, s12, 0x36780000
	s_addc_u32 s55, s13, 0
	v_ashrrev_i32_e32 v2, 8, v0
	s_add_u32 s68, s12, 0x367a0000
	v_lshlrev_b32_e32 v64, 5, v2
	s_addc_u32 s69, s13, 0
	v_ashrrev_i32_e32 v65, 31, v64
	s_add_u32 s70, s12, 0x367c0000
	v_cmp_eq_u32_e64 s[10:11], 1, v2
	v_lshlrev_b64 v[2:3], 18, v[64:65]
	v_or_b32_e32 v4, 1, v64
	v_or_b32_e32 v6, 2, v64
	v_or_b32_e32 v8, 3, v64
	v_or_b32_e32 v10, 4, v64
	v_or_b32_e32 v12, 5, v64
	v_or_b32_e32 v14, 6, v64
	v_or_b32_e32 v16, 7, v64
	v_or_b32_e32 v18, 8, v64
	v_or_b32_e32 v20, 9, v64
	v_or_b32_e32 v22, 10, v64
	v_or_b32_e32 v24, 11, v64
	v_or_b32_e32 v26, 12, v64
	v_or_b32_e32 v28, 13, v64
	v_or_b32_e32 v30, 14, v64
	v_or_b32_e32 v32, 15, v64
	v_or_b32_e32 v34, 16, v64
	v_or_b32_e32 v36, 17, v64
	v_or_b32_e32 v38, 18, v64
	v_or_b32_e32 v40, 19, v64
	v_or_b32_e32 v42, 20, v64
	v_or_b32_e32 v44, 21, v64
	v_or_b32_e32 v46, 22, v64
	v_or_b32_e32 v48, 23, v64
	v_or_b32_e32 v50, 24, v64
	v_or_b32_e32 v52, 25, v64
	v_or_b32_e32 v54, 26, v64
	v_or_b32_e32 v56, 27, v64
	v_or_b32_e32 v58, 28, v64
	v_or_b32_e32 v60, 29, v64
	v_or_b32_e32 v62, 30, v64
	v_or_b32_e32 v64, 31, v64
	s_addc_u32 s71, s13, 0
	v_and_b32_e32 v70, 0xff, v0
	s_movk_i32 s0, 0x100
	v_ashrrev_i32_e32 v5, 31, v4
	v_ashrrev_i32_e32 v7, 31, v6
	v_ashrrev_i32_e32 v9, 31, v8
	v_ashrrev_i32_e32 v11, 31, v10
	v_ashrrev_i32_e32 v13, 31, v12
	v_ashrrev_i32_e32 v15, 31, v14
	v_ashrrev_i32_e32 v17, 31, v16
	v_ashrrev_i32_e32 v19, 31, v18
	v_ashrrev_i32_e32 v21, 31, v20
	v_ashrrev_i32_e32 v23, 31, v22
	v_ashrrev_i32_e32 v25, 31, v24
	v_ashrrev_i32_e32 v27, 31, v26
	v_ashrrev_i32_e32 v29, 31, v28
	v_ashrrev_i32_e32 v31, 31, v30
	v_ashrrev_i32_e32 v33, 31, v32
	v_ashrrev_i32_e32 v35, 31, v34
	v_ashrrev_i32_e32 v37, 31, v36
	v_ashrrev_i32_e32 v39, 31, v38
	v_ashrrev_i32_e32 v41, 31, v40
	v_ashrrev_i32_e32 v43, 31, v42
	v_ashrrev_i32_e32 v45, 31, v44
	v_ashrrev_i32_e32 v47, 31, v46
	v_ashrrev_i32_e32 v49, 31, v48
	v_ashrrev_i32_e32 v51, 31, v50
	v_ashrrev_i32_e32 v53, 31, v52
	v_ashrrev_i32_e32 v55, 31, v54
	v_ashrrev_i32_e32 v57, 31, v56
	v_ashrrev_i32_e32 v59, 31, v58
	v_ashrrev_i32_e32 v61, 31, v60
	v_ashrrev_i32_e32 v63, 31, v62
	v_ashrrev_i32_e32 v65, 31, v64
	s_add_u32 s6, s12, 0x367e0000
	v_cmp_gt_u32_e64 s[8:9], s0, v0
	v_lshl_add_u32 v71, v70, 2, 0
	v_lshlrev_b64 v[4:5], 18, v[4:5]
	v_lshlrev_b64 v[6:7], 18, v[6:7]
	v_lshlrev_b64 v[8:9], 18, v[8:9]
	v_lshlrev_b64 v[10:11], 18, v[10:11]
	v_lshlrev_b64 v[12:13], 18, v[12:13]
	v_lshlrev_b64 v[14:15], 18, v[14:15]
	v_lshlrev_b64 v[16:17], 18, v[16:17]
	v_lshlrev_b64 v[18:19], 18, v[18:19]
	v_lshlrev_b64 v[20:21], 18, v[20:21]
	v_lshlrev_b64 v[22:23], 18, v[22:23]
	v_lshlrev_b64 v[24:25], 18, v[24:25]
	v_lshlrev_b64 v[26:27], 18, v[26:27]
	v_lshlrev_b64 v[28:29], 18, v[28:29]
	v_lshlrev_b64 v[30:31], 18, v[30:31]
	v_lshlrev_b64 v[32:33], 18, v[32:33]
	v_lshlrev_b64 v[34:35], 18, v[34:35]
	v_lshlrev_b64 v[36:37], 18, v[36:37]
	v_lshlrev_b64 v[38:39], 18, v[38:39]
	v_lshlrev_b64 v[40:41], 18, v[40:41]
	v_lshlrev_b64 v[42:43], 18, v[42:43]
	v_lshlrev_b64 v[44:45], 18, v[44:45]
	v_lshlrev_b64 v[46:47], 18, v[46:47]
	v_lshlrev_b64 v[48:49], 18, v[48:49]
	v_lshlrev_b64 v[50:51], 18, v[50:51]
	v_lshlrev_b64 v[52:53], 18, v[52:53]
	v_lshlrev_b64 v[54:55], 18, v[54:55]
	v_lshlrev_b64 v[56:57], 18, v[56:57]
	v_lshlrev_b64 v[58:59], 18, v[58:59]
	v_lshlrev_b64 v[60:61], 18, v[60:61]
	v_lshlrev_b64 v[62:63], 18, v[62:63]
	v_lshlrev_b64 v[64:65], 18, v[64:65]
	s_addc_u32 s7, s13, 0
	v_readlane_b32 s86, v254, 19
	s_branch .LBB0_415

; #define SEAM(k) do { if (IN((k) + 1)) { if (hi > N_PHASES) grid.sync();   else { XcdBarrier xb_; xb_.bar = (unsigned*)(ap->ws); xb_.x = xb_xcc_id(); xb_.st = (volatile LAS unsigned*)(lds_raw_las + LDS_BYTES - 16); xcd_barrier(xb_); } } } while (0)
; __device__ __forceinline__ void xcd_barrier(const XcdBarrier& b) {
;     asm volatile("s_waitcnt vmcnt(0)" ::: "memory");
;     __syncthreads();
;     if (threadIdx.x == 0) {
;         unsigned* bar = b.bar;
;         __builtin_amdgcn_s_waitcnt(0);
;         unsigned nloc = b.st[0], nx = b.st[1];
;         if (nloc == 0u) { xcd_barrier_complete(bar, b.x, nloc, nx); b.st[0] = nloc; b.st[1] = nx; }
; __global__ void __launch_bounds__(512, 2) fwd_mega(Args a) {
;     ...
;             SEAM(pb + 3); }
.LBB0_469:
	s_setprio 0
	v_readlane_b32 s0, v251, 6
	s_mul_i32 s0, s0, 7
	s_add_i32 s24, s0, 5
	s_cmp_lt_i32 s24, s45
	s_cbranch_scc0 .LBB0_482
	v_readlane_b32 s4, v254, 13
	v_readlane_b32 s5, v254, 14
	s_mov_b64 s[0:1], -1
	s_and_b64 vcc, exec, s[4:5]
	v_readlane_b32 s26, v251, 3
	s_cbranch_vccz .LBB0_525
	s_getreg_b32 s0, hwreg(HW_REG_XCC_ID, 0, 4)
	s_waitcnt vmcnt(0)
	s_waitcnt lgkmcnt(0)
	s_barrier
	s_mov_b64 s[4:5], exec
	v_readlane_b32 s6, v254, 4
	v_readlane_b32 s7, v254, 5
	s_and_b64 s[6:7], s[4:5], s[6:7]
	s_mov_b64 exec, s[6:7]
	s_cbranch_execz .LBB0_524
	v_readlane_b32 s1, v254, 49
	s_waitcnt vmcnt(0) expcnt(0) lgkmcnt(0)
	s_and_b32 s20, s0, 15
	v_mov_b32_e32 v0, s1
	ds_read_b32 v3, v0
	v_readlane_b32 s1, v254, 50
	s_waitcnt lgkmcnt(0)
	v_cmp_ne_u32_e32 vcc, 0, v3
	v_mov_b32_e32 v0, s1
	ds_read_b32 v2, v0
	s_cbranch_vccnz .LBB0_488
	s_add_u32 s0, s12, 0x1000
	s_addc_u32 s1, s13, 0
	s_add_u32 s6, s12, 0x1100
	s_addc_u32 s7, s13, 0
	s_add_u32 s8, s12, 0x1200
	s_addc_u32 s9, s13, 0
	s_add_u32 s10, s12, 0x1300
	s_addc_u32 s11, s13, 0
	s_mov_b32 s21, 1
	s_branch .LBB0_475
